# MLA epilogue: 64 serialized gate loads batched (all issued up front, one wait), saddr addressing
# speedup vs baseline: 1.0346x; 1.0109x over previous
.LBB0_299:
	s_or_b64 exec, exec, s[10:11]
	s_mul_i32 s8, s90, s71
	s_mul_hi_u32 s9, s90, s71
	s_mul_i32 s12, s91, s71
	s_add_u32 s9, s9, s12
	s_add_u32 s10, s80, s8
	s_addc_u32 s11, s81, s9
	s_lshl_b64 s[12:13], s[90:91], 12
	s_add_u32 s12, s12, s78
	s_addc_u32 s13, s13, s79
	s_mul_i32 s8, s71, 5
	v_lshrrev_b32_e32 v68, 5, v67
	v_or_b32_e32 v69, s74, v66
	v_lshlrev_b32_e32 v69, 1, v69
	v_mul_lo_u32 v72, v68, s71
	v_lshl_add_u32 v70, v68, 4, s93
	v_lshl_add_u32 v74, v68, 14, v69
	v_lshl_add_u32 v72, v72, 2, v69
	global_load_ushort v82, v72, s[10:11]
	global_load_ushort v83, v72, s[10:11] offset:64
	global_load_ushort v84, v72, s[10:11] offset:128
	global_load_ushort v85, v72, s[10:11] offset:192
	v_add_u32_e32 v72, s71, v72
	global_load_ushort v86, v72, s[10:11]
	global_load_ushort v87, v72, s[10:11] offset:64
	global_load_ushort v88, v72, s[10:11] offset:128
	global_load_ushort v89, v72, s[10:11] offset:192
	v_add_u32_e32 v72, s71, v72
	global_load_ushort v90, v72, s[10:11]
	global_load_ushort v91, v72, s[10:11] offset:64
	global_load_ushort v92, v72, s[10:11] offset:128
	global_load_ushort v93, v72, s[10:11] offset:192
	v_add_u32_e32 v72, s71, v72
	global_load_ushort v94, v72, s[10:11]
	global_load_ushort v95, v72, s[10:11] offset:64
	global_load_ushort v96, v72, s[10:11] offset:128
	global_load_ushort v97, v72, s[10:11] offset:192
	v_add_u32_e32 v72, s8, v72
	global_load_ushort v98, v72, s[10:11]
	global_load_ushort v99, v72, s[10:11] offset:64
	global_load_ushort v100, v72, s[10:11] offset:128
	global_load_ushort v101, v72, s[10:11] offset:192
	v_add_u32_e32 v72, s71, v72
	global_load_ushort v102, v72, s[10:11]
	global_load_ushort v103, v72, s[10:11] offset:64
	global_load_ushort v104, v72, s[10:11] offset:128
	global_load_ushort v105, v72, s[10:11] offset:192
	v_add_u32_e32 v72, s71, v72
	global_load_ushort v106, v72, s[10:11]
	global_load_ushort v107, v72, s[10:11] offset:64
	global_load_ushort v108, v72, s[10:11] offset:128
	global_load_ushort v109, v72, s[10:11] offset:192
	v_add_u32_e32 v72, s71, v72
	global_load_ushort v110, v72, s[10:11]
	global_load_ushort v111, v72, s[10:11] offset:64
	global_load_ushort v112, v72, s[10:11] offset:128
	global_load_ushort v113, v72, s[10:11] offset:192
	v_add_u32_e32 v72, s8, v72
	global_load_ushort v114, v72, s[10:11]
	global_load_ushort v115, v72, s[10:11] offset:64
	global_load_ushort v116, v72, s[10:11] offset:128
	global_load_ushort v117, v72, s[10:11] offset:192
	v_add_u32_e32 v72, s71, v72
	global_load_ushort v118, v72, s[10:11]
	global_load_ushort v119, v72, s[10:11] offset:64
	global_load_ushort v120, v72, s[10:11] offset:128
	global_load_ushort v121, v72, s[10:11] offset:192
	v_add_u32_e32 v72, s71, v72
	global_load_ushort v122, v72, s[10:11]
	global_load_ushort v123, v72, s[10:11] offset:64
	global_load_ushort v124, v72, s[10:11] offset:128
	global_load_ushort v125, v72, s[10:11] offset:192
	v_add_u32_e32 v72, s71, v72
	global_load_ushort v126, v72, s[10:11]
	global_load_ushort v127, v72, s[10:11] offset:64
	global_load_ushort v128, v72, s[10:11] offset:128
	global_load_ushort v129, v72, s[10:11] offset:192
	v_add_u32_e32 v72, s8, v72
	global_load_ushort v130, v72, s[10:11]
	global_load_ushort v131, v72, s[10:11] offset:64
	global_load_ushort v132, v72, s[10:11] offset:128
	global_load_ushort v133, v72, s[10:11] offset:192
	v_add_u32_e32 v72, s71, v72
	global_load_ushort v134, v72, s[10:11]
	global_load_ushort v135, v72, s[10:11] offset:64
	global_load_ushort v136, v72, s[10:11] offset:128
	global_load_ushort v137, v72, s[10:11] offset:192
	v_add_u32_e32 v72, s71, v72
	global_load_ushort v138, v72, s[10:11]
	global_load_ushort v139, v72, s[10:11] offset:64
	global_load_ushort v140, v72, s[10:11] offset:128
	global_load_ushort v141, v72, s[10:11] offset:192
	v_add_u32_e32 v72, s71, v72
	global_load_ushort v142, v72, s[10:11]
	global_load_ushort v143, v72, s[10:11] offset:64
	global_load_ushort v144, v72, s[10:11] offset:128
	global_load_ushort v145, v72, s[10:11] offset:192
	s_waitcnt lgkmcnt(0)
	ds_read_b128 v[212:215], v70
	ds_read_b128 v[216:219], v70 offset:32
	ds_read_b128 v[220:223], v70 offset:64
	ds_read_b128 v[224:227], v70 offset:96
	s_waitcnt lgkmcnt(0)
	v_rcp_f32_e32 v212, v212
	v_rcp_f32_e32 v213, v213
	v_rcp_f32_e32 v214, v214
	v_rcp_f32_e32 v215, v215
	v_rcp_f32_e32 v216, v216
	v_rcp_f32_e32 v217, v217
	v_rcp_f32_e32 v218, v218
	v_rcp_f32_e32 v219, v219
	v_rcp_f32_e32 v220, v220
	v_rcp_f32_e32 v221, v221
	v_rcp_f32_e32 v222, v222
	v_rcp_f32_e32 v223, v223
	v_rcp_f32_e32 v224, v224
	v_rcp_f32_e32 v225, v225
	v_rcp_f32_e32 v226, v226
	v_rcp_f32_e32 v227, v227
	v_mul_f32_e32 v50, v50, v212
	v_mul_f32_e32 v34, v34, v212
	v_mul_f32_e32 v18, v18, v212
	v_mul_f32_e32 v2, v2, v212
	v_mul_f32_e32 v51, v51, v213
	v_mul_f32_e32 v35, v35, v213
	v_mul_f32_e32 v19, v19, v213
	v_mul_f32_e32 v3, v3, v213
	v_mul_f32_e32 v52, v52, v214
	v_mul_f32_e32 v36, v36, v214
	v_mul_f32_e32 v20, v20, v214
	v_mul_f32_e32 v4, v4, v214
	v_mul_f32_e32 v53, v53, v215
	v_mul_f32_e32 v37, v37, v215
	v_mul_f32_e32 v21, v21, v215
	v_mul_f32_e32 v5, v5, v215
	v_mul_f32_e32 v54, v54, v216
	v_mul_f32_e32 v38, v38, v216
	v_mul_f32_e32 v22, v22, v216
	v_mul_f32_e32 v6, v6, v216
	v_mul_f32_e32 v55, v55, v217
	v_mul_f32_e32 v39, v39, v217
	v_mul_f32_e32 v23, v23, v217
	v_mul_f32_e32 v7, v7, v217
	v_mul_f32_e32 v56, v56, v218
	v_mul_f32_e32 v40, v40, v218
	v_mul_f32_e32 v24, v24, v218
	v_mul_f32_e32 v8, v8, v218
	v_mul_f32_e32 v57, v57, v219
	v_mul_f32_e32 v41, v41, v219
	v_mul_f32_e32 v25, v25, v219
	v_mul_f32_e32 v9, v9, v219
	v_mul_f32_e32 v58, v58, v220
	v_mul_f32_e32 v42, v42, v220
	v_mul_f32_e32 v26, v26, v220
	v_mul_f32_e32 v10, v10, v220
	v_mul_f32_e32 v59, v59, v221
	v_mul_f32_e32 v43, v43, v221
	v_mul_f32_e32 v27, v27, v221
	v_mul_f32_e32 v11, v11, v221
	v_mul_f32_e32 v60, v60, v222
	v_mul_f32_e32 v44, v44, v222
	v_mul_f32_e32 v28, v28, v222
	v_mul_f32_e32 v12, v12, v222
	v_mul_f32_e32 v61, v61, v223
	v_mul_f32_e32 v45, v45, v223
	v_mul_f32_e32 v29, v29, v223
	v_mul_f32_e32 v13, v13, v223
	v_mul_f32_e32 v62, v62, v224
	v_mul_f32_e32 v46, v46, v224
	v_mul_f32_e32 v30, v30, v224
	v_mul_f32_e32 v14, v14, v224
	v_mul_f32_e32 v63, v63, v225
	v_mul_f32_e32 v47, v47, v225
	v_mul_f32_e32 v31, v31, v225
	v_mul_f32_e32 v15, v15, v225
	v_mul_f32_e32 v64, v64, v226
	v_mul_f32_e32 v48, v48, v226
	v_mul_f32_e32 v32, v32, v226
	v_mul_f32_e32 v16, v16, v226
	v_mul_f32_e32 v65, v65, v227
	v_mul_f32_e32 v49, v49, v227
	v_mul_f32_e32 v33, v33, v227
	v_mul_f32_e32 v17, v17, v227
	s_waitcnt vmcnt(0)
	v_lshlrev_b32_e32 v82, 16, v82
	v_lshlrev_b32_e32 v83, 16, v83
	v_lshlrev_b32_e32 v84, 16, v84
	v_lshlrev_b32_e32 v85, 16, v85
	v_mul_f32_e32 v76, 0xbfb8aa3b, v82
	v_mul_f32_e32 v77, 0xbfb8aa3b, v83
	v_mul_f32_e32 v78, 0xbfb8aa3b, v84
	v_mul_f32_e32 v148, 0xbfb8aa3b, v85
	v_exp_f32_e32 v76, v76
	v_exp_f32_e32 v77, v77
	v_exp_f32_e32 v78, v78
	v_exp_f32_e32 v148, v148
	v_add_f32_e32 v76, 1.0, v76
	v_add_f32_e32 v77, 1.0, v77
	v_add_f32_e32 v78, 1.0, v78
	v_add_f32_e32 v148, 1.0, v148
	v_rcp_f32_e32 v76, v76
	v_rcp_f32_e32 v77, v77
	v_rcp_f32_e32 v78, v78
	v_rcp_f32_e32 v148, v148
	v_mul_f32_e32 v82, v76, v82
	v_mul_f32_e32 v83, v77, v83
	v_mul_f32_e32 v84, v78, v84
	v_mul_f32_e32 v85, v148, v85
	v_mul_f32_e32 v50, v50, v82
	v_mul_f32_e32 v34, v34, v83
	v_mul_f32_e32 v18, v18, v84
	v_mul_f32_e32 v2, v2, v85
	v_cvt_pk_bf16_f32 v50, v50, v149
	v_cvt_pk_bf16_f32 v34, v34, v149
	v_cvt_pk_bf16_f32 v18, v18, v149
	v_cvt_pk_bf16_f32 v2, v2, v149
	global_store_short v74, v50, s[12:13]
	global_store_short v74, v34, s[12:13] offset:64
	global_store_short v74, v18, s[12:13] offset:128
	global_store_short v74, v2, s[12:13] offset:192
	v_add_u32_e32 v74, 0x1000, v74
	v_lshlrev_b32_e32 v86, 16, v86
	v_lshlrev_b32_e32 v87, 16, v87
	v_lshlrev_b32_e32 v88, 16, v88
	v_lshlrev_b32_e32 v89, 16, v89
	v_mul_f32_e32 v76, 0xbfb8aa3b, v86
	v_mul_f32_e32 v77, 0xbfb8aa3b, v87
	v_mul_f32_e32 v78, 0xbfb8aa3b, v88
	v_mul_f32_e32 v148, 0xbfb8aa3b, v89
	v_exp_f32_e32 v76, v76
	v_exp_f32_e32 v77, v77
	v_exp_f32_e32 v78, v78
	v_exp_f32_e32 v148, v148
	v_add_f32_e32 v76, 1.0, v76
	v_add_f32_e32 v77, 1.0, v77
	v_add_f32_e32 v78, 1.0, v78
	v_add_f32_e32 v148, 1.0, v148
	v_rcp_f32_e32 v76, v76
	v_rcp_f32_e32 v77, v77
	v_rcp_f32_e32 v78, v78
	v_rcp_f32_e32 v148, v148
	v_mul_f32_e32 v86, v76, v86
	v_mul_f32_e32 v87, v77, v87
	v_mul_f32_e32 v88, v78, v88
	v_mul_f32_e32 v89, v148, v89
	v_mul_f32_e32 v51, v51, v86
	v_mul_f32_e32 v35, v35, v87
	v_mul_f32_e32 v19, v19, v88
	v_mul_f32_e32 v3, v3, v89
	v_cvt_pk_bf16_f32 v51, v51, v149
	v_cvt_pk_bf16_f32 v35, v35, v149
	v_cvt_pk_bf16_f32 v19, v19, v149
	v_cvt_pk_bf16_f32 v3, v3, v149
	global_store_short v74, v51, s[12:13]
	global_store_short v74, v35, s[12:13] offset:64
	global_store_short v74, v19, s[12:13] offset:128
	global_store_short v74, v3, s[12:13] offset:192
	v_add_u32_e32 v74, 0x1000, v74
	v_lshlrev_b32_e32 v90, 16, v90
	v_lshlrev_b32_e32 v91, 16, v91
	v_lshlrev_b32_e32 v92, 16, v92
	v_lshlrev_b32_e32 v93, 16, v93
	v_mul_f32_e32 v76, 0xbfb8aa3b, v90
	v_mul_f32_e32 v77, 0xbfb8aa3b, v91
	v_mul_f32_e32 v78, 0xbfb8aa3b, v92
	v_mul_f32_e32 v148, 0xbfb8aa3b, v93
	v_exp_f32_e32 v76, v76
	v_exp_f32_e32 v77, v77
	v_exp_f32_e32 v78, v78
	v_exp_f32_e32 v148, v148
	v_add_f32_e32 v76, 1.0, v76
	v_add_f32_e32 v77, 1.0, v77
	v_add_f32_e32 v78, 1.0, v78
	v_add_f32_e32 v148, 1.0, v148
	v_rcp_f32_e32 v76, v76
	v_rcp_f32_e32 v77, v77
	v_rcp_f32_e32 v78, v78
	v_rcp_f32_e32 v148, v148
	v_mul_f32_e32 v90, v76, v90
	v_mul_f32_e32 v91, v77, v91
	v_mul_f32_e32 v92, v78, v92
	v_mul_f32_e32 v93, v148, v93
	v_mul_f32_e32 v52, v52, v90
	v_mul_f32_e32 v36, v36, v91
	v_mul_f32_e32 v20, v20, v92
	v_mul_f32_e32 v4, v4, v93
	v_cvt_pk_bf16_f32 v52, v52, v149
	v_cvt_pk_bf16_f32 v36, v36, v149
	v_cvt_pk_bf16_f32 v20, v20, v149
	v_cvt_pk_bf16_f32 v4, v4, v149
	global_store_short v74, v52, s[12:13]
	global_store_short v74, v36, s[12:13] offset:64
	global_store_short v74, v20, s[12:13] offset:128
	global_store_short v74, v4, s[12:13] offset:192
	v_add_u32_e32 v74, 0x1000, v74
	v_lshlrev_b32_e32 v94, 16, v94
	v_lshlrev_b32_e32 v95, 16, v95
	v_lshlrev_b32_e32 v96, 16, v96
	v_lshlrev_b32_e32 v97, 16, v97
	v_mul_f32_e32 v76, 0xbfb8aa3b, v94
	v_mul_f32_e32 v77, 0xbfb8aa3b, v95
	v_mul_f32_e32 v78, 0xbfb8aa3b, v96
	v_mul_f32_e32 v148, 0xbfb8aa3b, v97
	v_exp_f32_e32 v76, v76
	v_exp_f32_e32 v77, v77
	v_exp_f32_e32 v78, v78
	v_exp_f32_e32 v148, v148
	v_add_f32_e32 v76, 1.0, v76
	v_add_f32_e32 v77, 1.0, v77
	v_add_f32_e32 v78, 1.0, v78
	v_add_f32_e32 v148, 1.0, v148
	v_rcp_f32_e32 v76, v76
	v_rcp_f32_e32 v77, v77
	v_rcp_f32_e32 v78, v78
	v_rcp_f32_e32 v148, v148
	v_mul_f32_e32 v94, v76, v94
	v_mul_f32_e32 v95, v77, v95
	v_mul_f32_e32 v96, v78, v96
	v_mul_f32_e32 v97, v148, v97
	v_mul_f32_e32 v53, v53, v94
	v_mul_f32_e32 v37, v37, v95
	v_mul_f32_e32 v21, v21, v96
	v_mul_f32_e32 v5, v5, v97
	v_cvt_pk_bf16_f32 v53, v53, v149
	v_cvt_pk_bf16_f32 v37, v37, v149
	v_cvt_pk_bf16_f32 v21, v21, v149
	v_cvt_pk_bf16_f32 v5, v5, v149
	global_store_short v74, v53, s[12:13]
	global_store_short v74, v37, s[12:13] offset:64
	global_store_short v74, v21, s[12:13] offset:128
	global_store_short v74, v5, s[12:13] offset:192
	v_add_u32_e32 v74, 0x5000, v74
	v_lshlrev_b32_e32 v98, 16, v98
	v_lshlrev_b32_e32 v99, 16, v99
	v_lshlrev_b32_e32 v100, 16, v100
	v_lshlrev_b32_e32 v101, 16, v101
	v_mul_f32_e32 v76, 0xbfb8aa3b, v98
	v_mul_f32_e32 v77, 0xbfb8aa3b, v99
	v_mul_f32_e32 v78, 0xbfb8aa3b, v100
	v_mul_f32_e32 v148, 0xbfb8aa3b, v101
	v_exp_f32_e32 v76, v76
	v_exp_f32_e32 v77, v77
	v_exp_f32_e32 v78, v78
	v_exp_f32_e32 v148, v148
	v_add_f32_e32 v76, 1.0, v76
	v_add_f32_e32 v77, 1.0, v77
	v_add_f32_e32 v78, 1.0, v78
	v_add_f32_e32 v148, 1.0, v148
	v_rcp_f32_e32 v76, v76
	v_rcp_f32_e32 v77, v77
	v_rcp_f32_e32 v78, v78
	v_rcp_f32_e32 v148, v148
	v_mul_f32_e32 v98, v76, v98
	v_mul_f32_e32 v99, v77, v99
	v_mul_f32_e32 v100, v78, v100
	v_mul_f32_e32 v101, v148, v101
	v_mul_f32_e32 v54, v54, v98
	v_mul_f32_e32 v38, v38, v99
	v_mul_f32_e32 v22, v22, v100
	v_mul_f32_e32 v6, v6, v101
	v_cvt_pk_bf16_f32 v54, v54, v149
	v_cvt_pk_bf16_f32 v38, v38, v149
	v_cvt_pk_bf16_f32 v22, v22, v149
	v_cvt_pk_bf16_f32 v6, v6, v149
	global_store_short v74, v54, s[12:13]
	global_store_short v74, v38, s[12:13] offset:64
	global_store_short v74, v22, s[12:13] offset:128
	global_store_short v74, v6, s[12:13] offset:192
	v_add_u32_e32 v74, 0x1000, v74
	v_lshlrev_b32_e32 v102, 16, v102
	v_lshlrev_b32_e32 v103, 16, v103
	v_lshlrev_b32_e32 v104, 16, v104
	v_lshlrev_b32_e32 v105, 16, v105
	v_mul_f32_e32 v76, 0xbfb8aa3b, v102
	v_mul_f32_e32 v77, 0xbfb8aa3b, v103
	v_mul_f32_e32 v78, 0xbfb8aa3b, v104
	v_mul_f32_e32 v148, 0xbfb8aa3b, v105
	v_exp_f32_e32 v76, v76
	v_exp_f32_e32 v77, v77
	v_exp_f32_e32 v78, v78
	v_exp_f32_e32 v148, v148
	v_add_f32_e32 v76, 1.0, v76
	v_add_f32_e32 v77, 1.0, v77
	v_add_f32_e32 v78, 1.0, v78
	v_add_f32_e32 v148, 1.0, v148
	v_rcp_f32_e32 v76, v76
	v_rcp_f32_e32 v77, v77
	v_rcp_f32_e32 v78, v78
	v_rcp_f32_e32 v148, v148
	v_mul_f32_e32 v102, v76, v102
	v_mul_f32_e32 v103, v77, v103
	v_mul_f32_e32 v104, v78, v104
	v_mul_f32_e32 v105, v148, v105
	v_mul_f32_e32 v55, v55, v102
	v_mul_f32_e32 v39, v39, v103
	v_mul_f32_e32 v23, v23, v104
	v_mul_f32_e32 v7, v7, v105
	v_cvt_pk_bf16_f32 v55, v55, v149
	v_cvt_pk_bf16_f32 v39, v39, v149
	v_cvt_pk_bf16_f32 v23, v23, v149
	v_cvt_pk_bf16_f32 v7, v7, v149
	global_store_short v74, v55, s[12:13]
	global_store_short v74, v39, s[12:13] offset:64
	global_store_short v74, v23, s[12:13] offset:128
	global_store_short v74, v7, s[12:13] offset:192
	v_add_u32_e32 v74, 0x1000, v74
	v_lshlrev_b32_e32 v106, 16, v106
	v_lshlrev_b32_e32 v107, 16, v107
	v_lshlrev_b32_e32 v108, 16, v108
	v_lshlrev_b32_e32 v109, 16, v109
	v_mul_f32_e32 v76, 0xbfb8aa3b, v106
	v_mul_f32_e32 v77, 0xbfb8aa3b, v107
	v_mul_f32_e32 v78, 0xbfb8aa3b, v108
	v_mul_f32_e32 v148, 0xbfb8aa3b, v109
	v_exp_f32_e32 v76, v76
	v_exp_f32_e32 v77, v77
	v_exp_f32_e32 v78, v78
	v_exp_f32_e32 v148, v148
	v_add_f32_e32 v76, 1.0, v76
	v_add_f32_e32 v77, 1.0, v77
	v_add_f32_e32 v78, 1.0, v78
	v_add_f32_e32 v148, 1.0, v148
	v_rcp_f32_e32 v76, v76
	v_rcp_f32_e32 v77, v77
	v_rcp_f32_e32 v78, v78
	v_rcp_f32_e32 v148, v148
	v_mul_f32_e32 v106, v76, v106
	v_mul_f32_e32 v107, v77, v107
	v_mul_f32_e32 v108, v78, v108
	v_mul_f32_e32 v109, v148, v109
	v_mul_f32_e32 v56, v56, v106
	v_mul_f32_e32 v40, v40, v107
	v_mul_f32_e32 v24, v24, v108
	v_mul_f32_e32 v8, v8, v109
	v_cvt_pk_bf16_f32 v56, v56, v149
	v_cvt_pk_bf16_f32 v40, v40, v149
	v_cvt_pk_bf16_f32 v24, v24, v149
	v_cvt_pk_bf16_f32 v8, v8, v149
	global_store_short v74, v56, s[12:13]
	global_store_short v74, v40, s[12:13] offset:64
	global_store_short v74, v24, s[12:13] offset:128
	global_store_short v74, v8, s[12:13] offset:192
	v_add_u32_e32 v74, 0x1000, v74
	v_lshlrev_b32_e32 v110, 16, v110
	v_lshlrev_b32_e32 v111, 16, v111
	v_lshlrev_b32_e32 v112, 16, v112
	v_lshlrev_b32_e32 v113, 16, v113
	v_mul_f32_e32 v76, 0xbfb8aa3b, v110
	v_mul_f32_e32 v77, 0xbfb8aa3b, v111
	v_mul_f32_e32 v78, 0xbfb8aa3b, v112
	v_mul_f32_e32 v148, 0xbfb8aa3b, v113
	v_exp_f32_e32 v76, v76
	v_exp_f32_e32 v77, v77
	v_exp_f32_e32 v78, v78
	v_exp_f32_e32 v148, v148
	v_add_f32_e32 v76, 1.0, v76
	v_add_f32_e32 v77, 1.0, v77
	v_add_f32_e32 v78, 1.0, v78
	v_add_f32_e32 v148, 1.0, v148
	v_rcp_f32_e32 v76, v76
	v_rcp_f32_e32 v77, v77
	v_rcp_f32_e32 v78, v78
	v_rcp_f32_e32 v148, v148
	v_mul_f32_e32 v110, v76, v110
	v_mul_f32_e32 v111, v77, v111
	v_mul_f32_e32 v112, v78, v112
	v_mul_f32_e32 v113, v148, v113
	v_mul_f32_e32 v57, v57, v110
	v_mul_f32_e32 v41, v41, v111
	v_mul_f32_e32 v25, v25, v112
	v_mul_f32_e32 v9, v9, v113
	v_cvt_pk_bf16_f32 v57, v57, v149
	v_cvt_pk_bf16_f32 v41, v41, v149
	v_cvt_pk_bf16_f32 v25, v25, v149
	v_cvt_pk_bf16_f32 v9, v9, v149
	global_store_short v74, v57, s[12:13]
	global_store_short v74, v41, s[12:13] offset:64
	global_store_short v74, v25, s[12:13] offset:128
	global_store_short v74, v9, s[12:13] offset:192
	v_add_u32_e32 v74, 0x5000, v74
	v_lshlrev_b32_e32 v114, 16, v114
	v_lshlrev_b32_e32 v115, 16, v115
	v_lshlrev_b32_e32 v116, 16, v116
	v_lshlrev_b32_e32 v117, 16, v117
	v_mul_f32_e32 v76, 0xbfb8aa3b, v114
	v_mul_f32_e32 v77, 0xbfb8aa3b, v115
	v_mul_f32_e32 v78, 0xbfb8aa3b, v116
	v_mul_f32_e32 v148, 0xbfb8aa3b, v117
	v_exp_f32_e32 v76, v76
	v_exp_f32_e32 v77, v77
	v_exp_f32_e32 v78, v78
	v_exp_f32_e32 v148, v148
	v_add_f32_e32 v76, 1.0, v76
	v_add_f32_e32 v77, 1.0, v77
	v_add_f32_e32 v78, 1.0, v78
	v_add_f32_e32 v148, 1.0, v148
	v_rcp_f32_e32 v76, v76
	v_rcp_f32_e32 v77, v77
	v_rcp_f32_e32 v78, v78
	v_rcp_f32_e32 v148, v148
	v_mul_f32_e32 v114, v76, v114
	v_mul_f32_e32 v115, v77, v115
	v_mul_f32_e32 v116, v78, v116
	v_mul_f32_e32 v117, v148, v117
	v_mul_f32_e32 v58, v58, v114
	v_mul_f32_e32 v42, v42, v115
	v_mul_f32_e32 v26, v26, v116
	v_mul_f32_e32 v10, v10, v117
	v_cvt_pk_bf16_f32 v58, v58, v149
	v_cvt_pk_bf16_f32 v42, v42, v149
	v_cvt_pk_bf16_f32 v26, v26, v149
	v_cvt_pk_bf16_f32 v10, v10, v149
	global_store_short v74, v58, s[12:13]
	global_store_short v74, v42, s[12:13] offset:64
	global_store_short v74, v26, s[12:13] offset:128
	global_store_short v74, v10, s[12:13] offset:192
	v_add_u32_e32 v74, 0x1000, v74
	v_lshlrev_b32_e32 v118, 16, v118
	v_lshlrev_b32_e32 v119, 16, v119
	v_lshlrev_b32_e32 v120, 16, v120
	v_lshlrev_b32_e32 v121, 16, v121
	v_mul_f32_e32 v76, 0xbfb8aa3b, v118
	v_mul_f32_e32 v77, 0xbfb8aa3b, v119
	v_mul_f32_e32 v78, 0xbfb8aa3b, v120
	v_mul_f32_e32 v148, 0xbfb8aa3b, v121
	v_exp_f32_e32 v76, v76
	v_exp_f32_e32 v77, v77
	v_exp_f32_e32 v78, v78
	v_exp_f32_e32 v148, v148
	v_add_f32_e32 v76, 1.0, v76
	v_add_f32_e32 v77, 1.0, v77
	v_add_f32_e32 v78, 1.0, v78
	v_add_f32_e32 v148, 1.0, v148
	v_rcp_f32_e32 v76, v76
	v_rcp_f32_e32 v77, v77
	v_rcp_f32_e32 v78, v78
	v_rcp_f32_e32 v148, v148
	v_mul_f32_e32 v118, v76, v118
	v_mul_f32_e32 v119, v77, v119
	v_mul_f32_e32 v120, v78, v120
	v_mul_f32_e32 v121, v148, v121
	v_mul_f32_e32 v59, v59, v118
	v_mul_f32_e32 v43, v43, v119
	v_mul_f32_e32 v27, v27, v120
	v_mul_f32_e32 v11, v11, v121
	v_cvt_pk_bf16_f32 v59, v59, v149
	v_cvt_pk_bf16_f32 v43, v43, v149
	v_cvt_pk_bf16_f32 v27, v27, v149
	v_cvt_pk_bf16_f32 v11, v11, v149
	global_store_short v74, v59, s[12:13]
	global_store_short v74, v43, s[12:13] offset:64
	global_store_short v74, v27, s[12:13] offset:128
	global_store_short v74, v11, s[12:13] offset:192
	v_add_u32_e32 v74, 0x1000, v74
	v_lshlrev_b32_e32 v122, 16, v122
	v_lshlrev_b32_e32 v123, 16, v123
	v_lshlrev_b32_e32 v124, 16, v124
	v_lshlrev_b32_e32 v125, 16, v125
	v_mul_f32_e32 v76, 0xbfb8aa3b, v122
	v_mul_f32_e32 v77, 0xbfb8aa3b, v123
	v_mul_f32_e32 v78, 0xbfb8aa3b, v124
	v_mul_f32_e32 v148, 0xbfb8aa3b, v125
	v_exp_f32_e32 v76, v76
	v_exp_f32_e32 v77, v77
	v_exp_f32_e32 v78, v78
	v_exp_f32_e32 v148, v148
	v_add_f32_e32 v76, 1.0, v76
	v_add_f32_e32 v77, 1.0, v77
	v_add_f32_e32 v78, 1.0, v78
	v_add_f32_e32 v148, 1.0, v148
	v_rcp_f32_e32 v76, v76
	v_rcp_f32_e32 v77, v77
	v_rcp_f32_e32 v78, v78
	v_rcp_f32_e32 v148, v148
	v_mul_f32_e32 v122, v76, v122
	v_mul_f32_e32 v123, v77, v123
	v_mul_f32_e32 v124, v78, v124
	v_mul_f32_e32 v125, v148, v125
	v_mul_f32_e32 v60, v60, v122
	v_mul_f32_e32 v44, v44, v123
	v_mul_f32_e32 v28, v28, v124
	v_mul_f32_e32 v12, v12, v125
	v_cvt_pk_bf16_f32 v60, v60, v149
	v_cvt_pk_bf16_f32 v44, v44, v149
	v_cvt_pk_bf16_f32 v28, v28, v149
	v_cvt_pk_bf16_f32 v12, v12, v149
	global_store_short v74, v60, s[12:13]
	global_store_short v74, v44, s[12:13] offset:64
	global_store_short v74, v28, s[12:13] offset:128
	global_store_short v74, v12, s[12:13] offset:192
	v_add_u32_e32 v74, 0x1000, v74
	v_lshlrev_b32_e32 v126, 16, v126
	v_lshlrev_b32_e32 v127, 16, v127
	v_lshlrev_b32_e32 v128, 16, v128
	v_lshlrev_b32_e32 v129, 16, v129
	v_mul_f32_e32 v76, 0xbfb8aa3b, v126
	v_mul_f32_e32 v77, 0xbfb8aa3b, v127
	v_mul_f32_e32 v78, 0xbfb8aa3b, v128
	v_mul_f32_e32 v148, 0xbfb8aa3b, v129
	v_exp_f32_e32 v76, v76
	v_exp_f32_e32 v77, v77
	v_exp_f32_e32 v78, v78
	v_exp_f32_e32 v148, v148
	v_add_f32_e32 v76, 1.0, v76
	v_add_f32_e32 v77, 1.0, v77
	v_add_f32_e32 v78, 1.0, v78
	v_add_f32_e32 v148, 1.0, v148
	v_rcp_f32_e32 v76, v76
	v_rcp_f32_e32 v77, v77
	v_rcp_f32_e32 v78, v78
	v_rcp_f32_e32 v148, v148
	v_mul_f32_e32 v126, v76, v126
	v_mul_f32_e32 v127, v77, v127
	v_mul_f32_e32 v128, v78, v128
	v_mul_f32_e32 v129, v148, v129
	v_mul_f32_e32 v61, v61, v126
	v_mul_f32_e32 v45, v45, v127
	v_mul_f32_e32 v29, v29, v128
	v_mul_f32_e32 v13, v13, v129
	v_cvt_pk_bf16_f32 v61, v61, v149
	v_cvt_pk_bf16_f32 v45, v45, v149
	v_cvt_pk_bf16_f32 v29, v29, v149
	v_cvt_pk_bf16_f32 v13, v13, v149
	global_store_short v74, v61, s[12:13]
	global_store_short v74, v45, s[12:13] offset:64
	global_store_short v74, v29, s[12:13] offset:128
	global_store_short v74, v13, s[12:13] offset:192
	v_add_u32_e32 v74, 0x5000, v74
	v_lshlrev_b32_e32 v130, 16, v130
	v_lshlrev_b32_e32 v131, 16, v131
	v_lshlrev_b32_e32 v132, 16, v132
	v_lshlrev_b32_e32 v133, 16, v133
	v_mul_f32_e32 v76, 0xbfb8aa3b, v130
	v_mul_f32_e32 v77, 0xbfb8aa3b, v131
	v_mul_f32_e32 v78, 0xbfb8aa3b, v132
	v_mul_f32_e32 v148, 0xbfb8aa3b, v133
	v_exp_f32_e32 v76, v76
	v_exp_f32_e32 v77, v77
	v_exp_f32_e32 v78, v78
	v_exp_f32_e32 v148, v148
	v_add_f32_e32 v76, 1.0, v76
	v_add_f32_e32 v77, 1.0, v77
	v_add_f32_e32 v78, 1.0, v78
	v_add_f32_e32 v148, 1.0, v148
	v_rcp_f32_e32 v76, v76
	v_rcp_f32_e32 v77, v77
	v_rcp_f32_e32 v78, v78
	v_rcp_f32_e32 v148, v148
	v_mul_f32_e32 v130, v76, v130
	v_mul_f32_e32 v131, v77, v131
	v_mul_f32_e32 v132, v78, v132
	v_mul_f32_e32 v133, v148, v133
	v_mul_f32_e32 v62, v62, v130
	v_mul_f32_e32 v46, v46, v131
	v_mul_f32_e32 v30, v30, v132
	v_mul_f32_e32 v14, v14, v133
	v_cvt_pk_bf16_f32 v62, v62, v149
	v_cvt_pk_bf16_f32 v46, v46, v149
	v_cvt_pk_bf16_f32 v30, v30, v149
	v_cvt_pk_bf16_f32 v14, v14, v149
	global_store_short v74, v62, s[12:13]
	global_store_short v74, v46, s[12:13] offset:64
	global_store_short v74, v30, s[12:13] offset:128
	global_store_short v74, v14, s[12:13] offset:192
	v_add_u32_e32 v74, 0x1000, v74
	v_lshlrev_b32_e32 v134, 16, v134
	v_lshlrev_b32_e32 v135, 16, v135
	v_lshlrev_b32_e32 v136, 16, v136
	v_lshlrev_b32_e32 v137, 16, v137
	v_mul_f32_e32 v76, 0xbfb8aa3b, v134
	v_mul_f32_e32 v77, 0xbfb8aa3b, v135
	v_mul_f32_e32 v78, 0xbfb8aa3b, v136
	v_mul_f32_e32 v148, 0xbfb8aa3b, v137
	v_exp_f32_e32 v76, v76
	v_exp_f32_e32 v77, v77
	v_exp_f32_e32 v78, v78
	v_exp_f32_e32 v148, v148
	v_add_f32_e32 v76, 1.0, v76
	v_add_f32_e32 v77, 1.0, v77
	v_add_f32_e32 v78, 1.0, v78
	v_add_f32_e32 v148, 1.0, v148
	v_rcp_f32_e32 v76, v76
	v_rcp_f32_e32 v77, v77
	v_rcp_f32_e32 v78, v78
	v_rcp_f32_e32 v148, v148
	v_mul_f32_e32 v134, v76, v134
	v_mul_f32_e32 v135, v77, v135
	v_mul_f32_e32 v136, v78, v136
	v_mul_f32_e32 v137, v148, v137
	v_mul_f32_e32 v63, v63, v134
	v_mul_f32_e32 v47, v47, v135
	v_mul_f32_e32 v31, v31, v136
	v_mul_f32_e32 v15, v15, v137
	v_cvt_pk_bf16_f32 v63, v63, v149
	v_cvt_pk_bf16_f32 v47, v47, v149
	v_cvt_pk_bf16_f32 v31, v31, v149
	v_cvt_pk_bf16_f32 v15, v15, v149
	global_store_short v74, v63, s[12:13]
	global_store_short v74, v47, s[12:13] offset:64
	global_store_short v74, v31, s[12:13] offset:128
	global_store_short v74, v15, s[12:13] offset:192
	v_add_u32_e32 v74, 0x1000, v74
	v_lshlrev_b32_e32 v138, 16, v138
	v_lshlrev_b32_e32 v139, 16, v139
	v_lshlrev_b32_e32 v140, 16, v140
	v_lshlrev_b32_e32 v141, 16, v141
	v_mul_f32_e32 v76, 0xbfb8aa3b, v138
	v_mul_f32_e32 v77, 0xbfb8aa3b, v139
	v_mul_f32_e32 v78, 0xbfb8aa3b, v140
	v_mul_f32_e32 v148, 0xbfb8aa3b, v141
	v_exp_f32_e32 v76, v76
	v_exp_f32_e32 v77, v77
	v_exp_f32_e32 v78, v78
	v_exp_f32_e32 v148, v148
	v_add_f32_e32 v76, 1.0, v76
	v_add_f32_e32 v77, 1.0, v77
	v_add_f32_e32 v78, 1.0, v78
	v_add_f32_e32 v148, 1.0, v148
	v_rcp_f32_e32 v76, v76
	v_rcp_f32_e32 v77, v77
	v_rcp_f32_e32 v78, v78
	v_rcp_f32_e32 v148, v148
	v_mul_f32_e32 v138, v76, v138
	v_mul_f32_e32 v139, v77, v139
	v_mul_f32_e32 v140, v78, v140
	v_mul_f32_e32 v141, v148, v141
	v_mul_f32_e32 v64, v64, v138
	v_mul_f32_e32 v48, v48, v139
	v_mul_f32_e32 v32, v32, v140
	v_mul_f32_e32 v16, v16, v141
	v_cvt_pk_bf16_f32 v64, v64, v149
	v_cvt_pk_bf16_f32 v48, v48, v149
	v_cvt_pk_bf16_f32 v32, v32, v149
	v_cvt_pk_bf16_f32 v16, v16, v149
	global_store_short v74, v64, s[12:13]
	global_store_short v74, v48, s[12:13] offset:64
	global_store_short v74, v32, s[12:13] offset:128
	global_store_short v74, v16, s[12:13] offset:192
	v_add_u32_e32 v74, 0x1000, v74
	v_lshlrev_b32_e32 v142, 16, v142
	v_lshlrev_b32_e32 v143, 16, v143
	v_lshlrev_b32_e32 v144, 16, v144
	v_lshlrev_b32_e32 v145, 16, v145
	v_mul_f32_e32 v76, 0xbfb8aa3b, v142
	v_mul_f32_e32 v77, 0xbfb8aa3b, v143
	v_mul_f32_e32 v78, 0xbfb8aa3b, v144
	v_mul_f32_e32 v148, 0xbfb8aa3b, v145
	v_exp_f32_e32 v76, v76
	v_exp_f32_e32 v77, v77
	v_exp_f32_e32 v78, v78
	v_exp_f32_e32 v148, v148
	v_add_f32_e32 v76, 1.0, v76
	v_add_f32_e32 v77, 1.0, v77
	v_add_f32_e32 v78, 1.0, v78
	v_add_f32_e32 v148, 1.0, v148
	v_rcp_f32_e32 v76, v76
	v_rcp_f32_e32 v77, v77
	v_rcp_f32_e32 v78, v78
	v_rcp_f32_e32 v148, v148
	v_mul_f32_e32 v142, v76, v142
	v_mul_f32_e32 v143, v77, v143
	v_mul_f32_e32 v144, v78, v144
	v_mul_f32_e32 v145, v148, v145
	v_mul_f32_e32 v65, v65, v142
	v_mul_f32_e32 v49, v49, v143
	v_mul_f32_e32 v33, v33, v144
	v_mul_f32_e32 v17, v17, v145
	v_cvt_pk_bf16_f32 v65, v65, v149
	v_cvt_pk_bf16_f32 v49, v49, v149
	v_cvt_pk_bf16_f32 v33, v33, v149
	v_cvt_pk_bf16_f32 v17, v17, v149
	global_store_short v74, v65, s[12:13]
	global_store_short v74, v49, s[12:13] offset:64
	global_store_short v74, v33, s[12:13] offset:128
	global_store_short v74, v17, s[12:13] offset:192
	s_and_b64 vcc, exec, s[88:89]
	s_mov_b64 s[8:9], 0
	s_waitcnt lgkmcnt(0)
	s_barrier
	s_cbranch_vccnz .LBB0_297
